# HGRN/mLSTM chunk scans (summaries + rec_output): DPP row-shift scan + readlane cross-row instead of 6-level ds_bpermute chain
# baseline (speedup 1.0000x reference)
; template <int MX, bool OUT>
; DI void rec_chunk(const Params& p, int l, int b, int h, int dir, int T0, unsigned char* smem, f32x4 (&St)[4], float& nst, float& dtot, int tid, const RecRaw& raw) {
;     ...
;   if (MX == 1) {
;     if (w == 0) {
;       float x = CUM[lane * 64];
; #pragma unroll
;       for (int o = 1; o < 64; o <<= 1) {
;         const float y = dir == 0 ? __shfl_up(x, o) : __shfl_down(x, o);
;         const bool ok = dir == 0 ? (lane >= o) : (lane + o < 64);
;         x += ok ? y : 0.f;
;       }
;       CUM[lane * 64] = x;
;     }
;     __syncthreads();
.LBB0_605:
	s_or_b64 exec, exec, s[0:1]
	s_waitcnt lgkmcnt(0)
	s_barrier
	s_and_saveexec_b64 s[46:47], s[6:7]
	s_cbranch_execz .LBB0_631
	ds_read_b32 v65, v150
	s_and_b64 vcc, exec, s[44:45]
	s_waitcnt lgkmcnt(0)
	s_cbranch_vccz .Lsc1_up
	v_add_f32_dpp v65, v65, v65 row_shl:1 row_mask:0xf bank_mask:0xf bound_ctrl:0
	s_nop 1
	v_add_f32_dpp v65, v65, v65 row_shl:2 row_mask:0xf bank_mask:0xf bound_ctrl:0
	s_nop 1
	v_add_f32_dpp v65, v65, v65 row_shl:4 row_mask:0xf bank_mask:0xf bound_ctrl:0
	s_nop 1
	v_add_f32_dpp v65, v65, v65 row_shl:8 row_mask:0xf bank_mask:0xf bound_ctrl:0
	s_nop 1
	v_readlane_b32 s0, v65, 48
	v_readlane_b32 s1, v65, 32
	v_readlane_b32 s48, v65, 16
	v_cmp_gt_u32_e32 vcc, 48, v79
	v_mov_b32_e32 v67, s0
	s_nop 1
	v_cndmask_b32_e32 v66, 0, v67, vcc
	v_add_f32_e32 v65, v65, v66
	v_cmp_gt_u32_e32 vcc, 32, v79
	v_mov_b32_e32 v67, s1
	s_nop 1
	v_cndmask_b32_e32 v66, 0, v67, vcc
	v_add_f32_e32 v65, v65, v66
	v_cmp_gt_u32_e32 vcc, 16, v79
	v_mov_b32_e32 v67, s48
	s_nop 1
	v_cndmask_b32_e32 v66, 0, v67, vcc
	v_add_f32_e32 v65, v65, v66
	s_branch .Lsc1_done
.Lsc1_up:
	v_add_f32_dpp v65, v65, v65 row_shr:1 row_mask:0xf bank_mask:0xf bound_ctrl:0
	s_nop 1
	v_add_f32_dpp v65, v65, v65 row_shr:2 row_mask:0xf bank_mask:0xf bound_ctrl:0
	s_nop 1
	v_add_f32_dpp v65, v65, v65 row_shr:4 row_mask:0xf bank_mask:0xf bound_ctrl:0
	s_nop 1
	v_add_f32_dpp v65, v65, v65 row_shr:8 row_mask:0xf bank_mask:0xf bound_ctrl:0
	s_nop 1
	v_readlane_b32 s0, v65, 15
	v_readlane_b32 s1, v65, 31
	v_readlane_b32 s48, v65, 47
	v_cmp_lt_u32_e32 vcc, 15, v79
	v_mov_b32_e32 v67, s0
	s_nop 1
	v_cndmask_b32_e32 v66, 0, v67, vcc
	v_add_f32_e32 v65, v65, v66
	v_cmp_lt_u32_e32 vcc, 31, v79
	v_mov_b32_e32 v67, s1
	s_nop 1
	v_cndmask_b32_e32 v66, 0, v67, vcc
	v_add_f32_e32 v65, v65, v66
	v_cmp_lt_u32_e32 vcc, 47, v79
	v_mov_b32_e32 v67, s48
	s_nop 1
	v_cndmask_b32_e32 v66, 0, v67, vcc
	v_add_f32_e32 v65, v65, v66
.Lsc1_done:
	ds_write_b32 v150, v65

; template <int MX, bool OUT>
; DI void rec_chunk(const Params& p, int l, int b, int h, int dir, int T0, unsigned char* smem, f32x4 (&St)[4], float& nst, float& dtot, int tid, const RecRaw& raw) {
;     ...
;   if (MX == 1) {
;     if (w == 0) {
;       float x = CUM[lane * 64];
; #pragma unroll
;       for (int o = 1; o < 64; o <<= 1) {
;         const float y = dir == 0 ? __shfl_up(x, o) : __shfl_down(x, o);
;         const bool ok = dir == 0 ? (lane >= o) : (lane + o < 64);
;         x += ok ? y : 0.f;
;       }
;       CUM[lane * 64] = x;
;     }
;     __syncthreads();
.LBB0_850:
	s_or_b64 exec, exec, s[0:1]
	s_waitcnt lgkmcnt(0)
	s_barrier
	s_and_saveexec_b64 s[44:45], s[6:7]
	s_cbranch_execz .LBB0_876
	ds_read_b32 v65, v154
	s_and_b64 vcc, exec, s[12:13]
	s_waitcnt lgkmcnt(0)
	s_cbranch_vccz .Lsc2_up
	v_add_f32_dpp v65, v65, v65 row_shl:1 row_mask:0xf bank_mask:0xf bound_ctrl:0
	s_nop 1
	v_add_f32_dpp v65, v65, v65 row_shl:2 row_mask:0xf bank_mask:0xf bound_ctrl:0
	s_nop 1
	v_add_f32_dpp v65, v65, v65 row_shl:4 row_mask:0xf bank_mask:0xf bound_ctrl:0
	s_nop 1
	v_add_f32_dpp v65, v65, v65 row_shl:8 row_mask:0xf bank_mask:0xf bound_ctrl:0
	s_nop 1
	v_readlane_b32 s0, v65, 48
	v_readlane_b32 s1, v65, 32
	v_readlane_b32 s46, v65, 16
	v_cmp_gt_u32_e32 vcc, 48, v81
	v_mov_b32_e32 v67, s0
	s_nop 1
	v_cndmask_b32_e32 v66, 0, v67, vcc
	v_add_f32_e32 v65, v65, v66
	v_cmp_gt_u32_e32 vcc, 32, v81
	v_mov_b32_e32 v67, s1
	s_nop 1
	v_cndmask_b32_e32 v66, 0, v67, vcc
	v_add_f32_e32 v65, v65, v66
	v_cmp_gt_u32_e32 vcc, 16, v81
	v_mov_b32_e32 v67, s46
	s_nop 1
	v_cndmask_b32_e32 v66, 0, v67, vcc
	v_add_f32_e32 v65, v65, v66
	s_branch .Lsc2_done
.Lsc2_up:
	v_add_f32_dpp v65, v65, v65 row_shr:1 row_mask:0xf bank_mask:0xf bound_ctrl:0
	s_nop 1
	v_add_f32_dpp v65, v65, v65 row_shr:2 row_mask:0xf bank_mask:0xf bound_ctrl:0
	s_nop 1
	v_add_f32_dpp v65, v65, v65 row_shr:4 row_mask:0xf bank_mask:0xf bound_ctrl:0
	s_nop 1
	v_add_f32_dpp v65, v65, v65 row_shr:8 row_mask:0xf bank_mask:0xf bound_ctrl:0
	s_nop 1
	v_readlane_b32 s0, v65, 15
	v_readlane_b32 s1, v65, 31
	v_readlane_b32 s46, v65, 47
	v_cmp_lt_u32_e32 vcc, 15, v81
	v_mov_b32_e32 v67, s0
	s_nop 1
	v_cndmask_b32_e32 v66, 0, v67, vcc
	v_add_f32_e32 v65, v65, v66
	v_cmp_lt_u32_e32 vcc, 31, v81
	v_mov_b32_e32 v67, s1
	s_nop 1
	v_cndmask_b32_e32 v66, 0, v67, vcc
	v_add_f32_e32 v65, v65, v66
	v_cmp_lt_u32_e32 vcc, 47, v81
	v_mov_b32_e32 v67, s46
	s_nop 1
	v_cndmask_b32_e32 v66, 0, v67, vcc
	v_add_f32_e32 v65, v65, v66
.Lsc2_done:
	ds_write_b32 v154, v65
